# GEMM K-loops: only the loop-carried scalar updates and exit test moved in front of the loop-back barrier (loop head untouched)
# speedup vs baseline: 1.0047x; 1.0047x over previous
.LBB0_29:
	s_add_u32 s12, s0, 0xfffc0080
	s_addc_u32 s13, s1, -1
	s_add_i32 s14, 0, 0x10000
	s_cmp_eq_u32 s11, 12
	s_cselect_b32 s37, s5, s13
	s_cselect_b32 s36, s6, s12
	s_cselect_b32 s29, s7, s10
	s_cselect_b32 s28, s8, s9
	s_add_i32 s15, 0, 0x14000
	v_add_u32_e32 v142, s14, v179
	v_add_u32_e32 v168, s15, v179
	ds_read_b128 v[130:133], v142
	ds_read_b128 v[134:137], v142 offset:1024
	ds_read_b128 v[138:141], v142 offset:2048
	ds_read_b128 v[142:145], v142 offset:3072
	ds_read_b128 v[146:149], v168
	ds_read_b128 v[160:163], v168 offset:1024
	ds_read_b128 v[164:167], v168 offset:2048
	ds_read_b128 v[168:171], v168 offset:3072
	s_mov_b32 m0, s80
	v_lshl_add_u64 v[208:209], s[0:1], 0, v[156:157]
	ds_read_b128 v[172:175], v182
	ds_read_b128 v[184:187], v182 offset:1024
	ds_read_b128 v[188:191], v182 offset:2048
	ds_read_b128 v[192:195], v182 offset:3072
	ds_read_b128 v[196:199], v182 offset:4096
	ds_read_b128 v[200:203], v182 offset:5120
	ds_read_b128 v[204:207], v182 offset:6144
	ds_read_b128 v[226:229], v182 offset:7168
	global_load_lds_dwordx4 v[208:209], off
	v_lshl_add_u64 v[208:209], s[0:1], 0, v[158:159]
	s_add_i32 m0, s25, 0xe000
	s_nop 0
	global_load_lds_dwordx4 v[208:209], off
	s_waitcnt vmcnt(8)
	s_waitcnt lgkmcnt(0)
	s_barrier
	s_setprio 1
	s_waitcnt lgkmcnt(0)
	v_mfma_f32_16x16x32_bf16 v[126:129], v[130:133], v[172:175], v[126:129]
	v_mfma_f32_16x16x32_bf16 v[122:125], v[138:141], v[172:175], v[122:125]
	v_mfma_f32_16x16x32_bf16 v[110:113], v[130:133], v[188:191], v[110:113]
	v_mfma_f32_16x16x32_bf16 v[106:109], v[138:141], v[188:191], v[106:109]
	v_mfma_f32_16x16x32_bf16 v[94:97], v[130:133], v[196:199], v[94:97]
	v_mfma_f32_16x16x32_bf16 v[90:93], v[138:141], v[196:199], v[90:93]
	v_mfma_f32_16x16x32_bf16 v[78:81], v[130:133], v[204:207], v[78:81]
	v_mfma_f32_16x16x32_bf16 v[74:77], v[138:141], v[204:207], v[74:77]
	v_mfma_f32_16x16x32_bf16 v[126:129], v[134:137], v[184:187], v[126:129]
	v_mfma_f32_16x16x32_bf16 v[122:125], v[142:145], v[184:187], v[122:125]
	v_mfma_f32_16x16x32_bf16 v[110:113], v[134:137], v[192:195], v[110:113]
	v_mfma_f32_16x16x32_bf16 v[106:109], v[142:145], v[192:195], v[106:109]
	v_mfma_f32_16x16x32_bf16 v[94:97], v[134:137], v[200:203], v[94:97]
	v_mfma_f32_16x16x32_bf16 v[90:93], v[142:145], v[200:203], v[90:93]
	v_mfma_f32_16x16x32_bf16 v[78:81], v[134:137], v[226:229], v[78:81]
	v_mfma_f32_16x16x32_bf16 v[74:77], v[142:145], v[226:229], v[74:77]
	s_setprio 0
	s_setprio 1
	v_mfma_f32_16x16x32_bf16 v[118:121], v[146:149], v[172:175], v[118:121]
	v_mfma_f32_16x16x32_bf16 v[114:117], v[164:167], v[172:175], v[114:117]
	v_mfma_f32_16x16x32_bf16 v[102:105], v[146:149], v[188:191], v[102:105]
	v_mfma_f32_16x16x32_bf16 v[98:101], v[164:167], v[188:191], v[98:101]
	v_mfma_f32_16x16x32_bf16 v[86:89], v[146:149], v[196:199], v[86:89]
	v_mfma_f32_16x16x32_bf16 v[82:85], v[164:167], v[196:199], v[82:85]
	v_mfma_f32_16x16x32_bf16 v[70:73], v[146:149], v[204:207], v[70:73]
	v_mfma_f32_16x16x32_bf16 v[66:69], v[164:167], v[204:207], v[66:69]
	v_mfma_f32_16x16x32_bf16 v[118:121], v[160:163], v[184:187], v[118:121]
	v_mfma_f32_16x16x32_bf16 v[114:117], v[168:171], v[184:187], v[114:117]
	v_mfma_f32_16x16x32_bf16 v[102:105], v[160:163], v[192:195], v[102:105]
	v_mfma_f32_16x16x32_bf16 v[98:101], v[168:171], v[192:195], v[98:101]
	v_mfma_f32_16x16x32_bf16 v[86:89], v[160:163], v[200:203], v[86:89]
	v_mfma_f32_16x16x32_bf16 v[82:85], v[168:171], v[200:203], v[82:85]
	v_mfma_f32_16x16x32_bf16 v[70:73], v[160:163], v[226:229], v[70:73]
	v_mfma_f32_16x16x32_bf16 v[66:69], v[168:171], v[226:229], v[66:69]
	s_setprio 0
	s_barrier
	s_add_i32 s12, s14, s38
	v_lshl_add_u64 v[208:209], s[28:29], 0, v[64:65]
	s_mov_b32 m0, s12
	ds_read_b128 v[172:175], v182 offset:16384
	ds_read_b128 v[184:187], v182 offset:17408
	ds_read_b128 v[188:191], v182 offset:18432
	ds_read_b128 v[192:195], v182 offset:19456
	ds_read_b128 v[196:199], v182 offset:20480
	ds_read_b128 v[200:203], v182 offset:21504
	ds_read_b128 v[204:207], v182 offset:22528
	ds_read_b128 v[226:229], v182 offset:23552
	global_load_lds_dwordx4 v[208:209], off
	s_add_i32 m0, s12, 0x2000
	s_add_u32 s12, s28, 0x40000
	v_lshl_add_u64 v[210:211], s[28:29], 0, v[150:151]
	s_addc_u32 s13, s29, 0
	s_add_i32 s14, s15, s38
	global_load_lds_dwordx4 v[210:211], off
	v_lshl_add_u64 v[212:213], s[12:13], 0, v[64:65]
	s_mov_b32 m0, s14
	v_lshl_add_u64 v[218:219], s[36:37], 0, v[152:153]
	global_load_lds_dwordx4 v[212:213], off
	v_lshl_add_u64 v[212:213], s[12:13], 0, v[150:151]
	s_add_i32 m0, s14, 0x2000
	v_readlane_b32 s12, v251, 21
	global_load_lds_dwordx4 v[212:213], off
	v_lshl_add_u64 v[212:213], s[36:37], 0, v[154:155]
	s_mov_b32 m0, s25
	s_nop 0
	global_load_lds_dwordx4 v[212:213], off
	s_mov_b32 m0, s12
	s_nop 0
	global_load_lds_dwordx4 v[218:219], off
	s_waitcnt vmcnt(8)
	s_waitcnt lgkmcnt(0)
	s_barrier
	s_setprio 1
	s_waitcnt lgkmcnt(0)
	v_mfma_f32_16x16x32_bf16 v[60:63], v[130:133], v[172:175], v[60:63]
	v_mfma_f32_16x16x32_bf16 v[56:59], v[138:141], v[172:175], v[56:59]
	v_mfma_f32_16x16x32_bf16 v[44:47], v[130:133], v[188:191], v[44:47]
	v_mfma_f32_16x16x32_bf16 v[40:43], v[138:141], v[188:191], v[40:43]
	v_mfma_f32_16x16x32_bf16 v[28:31], v[130:133], v[196:199], v[28:31]
	v_mfma_f32_16x16x32_bf16 v[24:27], v[138:141], v[196:199], v[24:27]
	v_mfma_f32_16x16x32_bf16 v[12:15], v[130:133], v[204:207], v[12:15]
	v_mfma_f32_16x16x32_bf16 v[8:11], v[138:141], v[204:207], v[8:11]
	v_mfma_f32_16x16x32_bf16 v[60:63], v[134:137], v[184:187], v[60:63]
	v_mfma_f32_16x16x32_bf16 v[56:59], v[142:145], v[184:187], v[56:59]
	v_mfma_f32_16x16x32_bf16 v[44:47], v[134:137], v[192:195], v[44:47]
	v_mfma_f32_16x16x32_bf16 v[40:43], v[142:145], v[192:195], v[40:43]
	v_mfma_f32_16x16x32_bf16 v[28:31], v[134:137], v[200:203], v[28:31]
	v_mfma_f32_16x16x32_bf16 v[24:27], v[142:145], v[200:203], v[24:27]
	v_mfma_f32_16x16x32_bf16 v[12:15], v[134:137], v[226:229], v[12:15]
	v_mfma_f32_16x16x32_bf16 v[8:11], v[142:145], v[226:229], v[8:11]
	s_setprio 0
	s_setprio 1
	v_mfma_f32_16x16x32_bf16 v[52:55], v[146:149], v[172:175], v[52:55]
	v_mfma_f32_16x16x32_bf16 v[48:51], v[164:167], v[172:175], v[48:51]
	v_mfma_f32_16x16x32_bf16 v[36:39], v[146:149], v[188:191], v[36:39]
	v_mfma_f32_16x16x32_bf16 v[32:35], v[164:167], v[188:191], v[32:35]
	v_mfma_f32_16x16x32_bf16 v[20:23], v[146:149], v[196:199], v[20:23]
	v_mfma_f32_16x16x32_bf16 v[16:19], v[164:167], v[196:199], v[16:19]
	v_mfma_f32_16x16x32_bf16 v[4:7], v[146:149], v[204:207], v[4:7]
	v_mfma_f32_16x16x32_bf16 v[0:3], v[164:167], v[204:207], v[0:3]
	v_mfma_f32_16x16x32_bf16 v[52:55], v[160:163], v[184:187], v[52:55]
	v_mfma_f32_16x16x32_bf16 v[48:51], v[168:171], v[184:187], v[48:51]
	v_mfma_f32_16x16x32_bf16 v[36:39], v[160:163], v[192:195], v[36:39]
	v_mfma_f32_16x16x32_bf16 v[32:35], v[168:171], v[192:195], v[32:35]
	v_mfma_f32_16x16x32_bf16 v[20:23], v[160:163], v[200:203], v[20:23]
	v_mfma_f32_16x16x32_bf16 v[16:19], v[168:171], v[200:203], v[16:19]
	v_mfma_f32_16x16x32_bf16 v[4:7], v[160:163], v[226:229], v[4:7]
	v_mfma_f32_16x16x32_bf16 v[0:3], v[168:171], v[226:229], v[0:3]
	s_setprio 0
	s_barrier
	s_add_i32 s14, 0, 0x18000
	s_add_i32 s15, 0, 0x1c000
	v_add_u32_e32 v142, s14, v179
	v_add_u32_e32 v168, s15, v179
	ds_read_b128 v[130:133], v142
	ds_read_b128 v[134:137], v142 offset:1024
	ds_read_b128 v[138:141], v142 offset:2048
	ds_read_b128 v[142:145], v142 offset:3072
	ds_read_b128 v[146:149], v168
	ds_read_b128 v[160:163], v168 offset:1024
	ds_read_b128 v[164:167], v168 offset:2048
	ds_read_b128 v[168:171], v168 offset:3072
	s_add_u32 s12, s36, 0x40000
	s_addc_u32 s13, s37, 0
	s_mov_b32 m0, s75
	v_lshl_add_u64 v[230:231], s[12:13], 0, v[154:155]
	ds_read_b128 v[172:175], v182 offset:32768
	ds_read_b128 v[184:187], v182 offset:33792
	ds_read_b128 v[188:191], v182 offset:34816
	ds_read_b128 v[192:195], v182 offset:35840
	ds_read_b128 v[196:199], v182 offset:36864
	ds_read_b128 v[200:203], v182 offset:37888
	ds_read_b128 v[204:207], v182 offset:38912
	ds_read_b128 v[226:229], v182 offset:39936
	global_load_lds_dwordx4 v[230:231], off
	v_lshl_add_u64 v[230:231], s[12:13], 0, v[152:153]
	s_mov_b32 m0, s74
	s_nop 0
	global_load_lds_dwordx4 v[230:231], off
	s_waitcnt vmcnt(8)
	s_waitcnt lgkmcnt(0)
	s_barrier
	s_setprio 1
	s_waitcnt lgkmcnt(0)
	v_mfma_f32_16x16x32_bf16 v[126:129], v[130:133], v[172:175], v[126:129]
	v_mfma_f32_16x16x32_bf16 v[122:125], v[138:141], v[172:175], v[122:125]
	v_mfma_f32_16x16x32_bf16 v[110:113], v[130:133], v[188:191], v[110:113]
	v_mfma_f32_16x16x32_bf16 v[106:109], v[138:141], v[188:191], v[106:109]
	v_mfma_f32_16x16x32_bf16 v[94:97], v[130:133], v[196:199], v[94:97]
	v_mfma_f32_16x16x32_bf16 v[90:93], v[138:141], v[196:199], v[90:93]
	v_mfma_f32_16x16x32_bf16 v[78:81], v[130:133], v[204:207], v[78:81]
	v_mfma_f32_16x16x32_bf16 v[74:77], v[138:141], v[204:207], v[74:77]
	v_mfma_f32_16x16x32_bf16 v[126:129], v[134:137], v[184:187], v[126:129]
	v_mfma_f32_16x16x32_bf16 v[122:125], v[142:145], v[184:187], v[122:125]
	v_mfma_f32_16x16x32_bf16 v[110:113], v[134:137], v[192:195], v[110:113]
	v_mfma_f32_16x16x32_bf16 v[106:109], v[142:145], v[192:195], v[106:109]
	v_mfma_f32_16x16x32_bf16 v[94:97], v[134:137], v[200:203], v[94:97]
	v_mfma_f32_16x16x32_bf16 v[90:93], v[142:145], v[200:203], v[90:93]
	v_mfma_f32_16x16x32_bf16 v[78:81], v[134:137], v[226:229], v[78:81]
	v_mfma_f32_16x16x32_bf16 v[74:77], v[142:145], v[226:229], v[74:77]
	s_setprio 0
	s_setprio 1
	v_mfma_f32_16x16x32_bf16 v[118:121], v[146:149], v[172:175], v[118:121]
	v_mfma_f32_16x16x32_bf16 v[114:117], v[164:167], v[172:175], v[114:117]
	v_mfma_f32_16x16x32_bf16 v[102:105], v[146:149], v[188:191], v[102:105]
	v_mfma_f32_16x16x32_bf16 v[98:101], v[164:167], v[188:191], v[98:101]
	v_mfma_f32_16x16x32_bf16 v[86:89], v[146:149], v[196:199], v[86:89]
	v_mfma_f32_16x16x32_bf16 v[82:85], v[164:167], v[196:199], v[82:85]
	v_mfma_f32_16x16x32_bf16 v[70:73], v[146:149], v[204:207], v[70:73]
	v_mfma_f32_16x16x32_bf16 v[66:69], v[164:167], v[204:207], v[66:69]
	v_mfma_f32_16x16x32_bf16 v[118:121], v[160:163], v[184:187], v[118:121]
	v_mfma_f32_16x16x32_bf16 v[114:117], v[168:171], v[184:187], v[114:117]
	v_mfma_f32_16x16x32_bf16 v[102:105], v[160:163], v[192:195], v[102:105]
	v_mfma_f32_16x16x32_bf16 v[98:101], v[168:171], v[192:195], v[98:101]
	v_mfma_f32_16x16x32_bf16 v[86:89], v[160:163], v[200:203], v[86:89]
	v_mfma_f32_16x16x32_bf16 v[82:85], v[168:171], v[200:203], v[82:85]
	v_mfma_f32_16x16x32_bf16 v[70:73], v[160:163], v[226:229], v[70:73]
	v_mfma_f32_16x16x32_bf16 v[66:69], v[168:171], v[226:229], v[66:69]
	s_setprio 0
	s_barrier
	s_add_i32 s12, s14, s38
	v_lshl_add_u64 v[208:209], v[208:209], 0, s[40:41]
	s_mov_b32 m0, s12
	ds_read_b128 v[172:175], v182 offset:49152
	ds_read_b128 v[184:187], v182 offset:50176
	ds_read_b128 v[188:191], v182 offset:51200
	ds_read_b128 v[192:195], v182 offset:52224
	ds_read_b128 v[196:199], v182 offset:53248
	ds_read_b128 v[200:203], v182 offset:54272
	ds_read_b128 v[204:207], v182 offset:55296
	ds_read_b128 v[226:229], v182 offset:56320
	global_load_lds_dwordx4 v[208:209], off
	s_add_i32 m0, s12, 0x2000
	s_add_u32 s12, s28, 0x40080
	v_lshl_add_u64 v[208:209], v[210:211], 0, s[40:41]
	s_addc_u32 s13, s29, 0
	s_add_i32 s14, s15, s38
	global_load_lds_dwordx4 v[208:209], off
	v_lshl_add_u64 v[208:209], s[12:13], 0, v[64:65]
	s_mov_b32 m0, s14
	s_nop 0
	global_load_lds_dwordx4 v[208:209], off
	v_lshl_add_u64 v[208:209], s[12:13], 0, v[150:151]
	s_add_i32 m0, s14, 0x2000
	s_nop 0
	global_load_lds_dwordx4 v[208:209], off
	v_lshl_add_u64 v[208:209], v[212:213], 0, s[40:41]
	s_mov_b32 m0, s92
	s_nop 0
	global_load_lds_dwordx4 v[208:209], off
	v_lshl_add_u64 v[208:209], v[218:219], 0, s[40:41]
	s_mov_b32 m0, s78
	s_nop 0
	global_load_lds_dwordx4 v[208:209], off
	s_waitcnt vmcnt(8)
	s_waitcnt lgkmcnt(0)
	s_barrier
	s_setprio 1
	s_waitcnt lgkmcnt(0)
	v_mfma_f32_16x16x32_bf16 v[60:63], v[130:133], v[172:175], v[60:63]
	v_mfma_f32_16x16x32_bf16 v[56:59], v[138:141], v[172:175], v[56:59]
	v_mfma_f32_16x16x32_bf16 v[44:47], v[130:133], v[188:191], v[44:47]
	v_mfma_f32_16x16x32_bf16 v[40:43], v[138:141], v[188:191], v[40:43]
	v_mfma_f32_16x16x32_bf16 v[28:31], v[130:133], v[196:199], v[28:31]
	v_mfma_f32_16x16x32_bf16 v[24:27], v[138:141], v[196:199], v[24:27]
	v_mfma_f32_16x16x32_bf16 v[12:15], v[130:133], v[204:207], v[12:15]
	v_mfma_f32_16x16x32_bf16 v[8:11], v[138:141], v[204:207], v[8:11]
	v_mfma_f32_16x16x32_bf16 v[60:63], v[134:137], v[184:187], v[60:63]
	v_mfma_f32_16x16x32_bf16 v[56:59], v[142:145], v[184:187], v[56:59]
	v_mfma_f32_16x16x32_bf16 v[44:47], v[134:137], v[192:195], v[44:47]
	v_mfma_f32_16x16x32_bf16 v[40:43], v[142:145], v[192:195], v[40:43]
	v_mfma_f32_16x16x32_bf16 v[28:31], v[134:137], v[200:203], v[28:31]
	v_mfma_f32_16x16x32_bf16 v[24:27], v[142:145], v[200:203], v[24:27]
	v_mfma_f32_16x16x32_bf16 v[12:15], v[134:137], v[226:229], v[12:15]
	v_mfma_f32_16x16x32_bf16 v[8:11], v[142:145], v[226:229], v[8:11]
	s_setprio 0
	s_setprio 1
	v_mfma_f32_16x16x32_bf16 v[52:55], v[146:149], v[172:175], v[52:55]
	v_mfma_f32_16x16x32_bf16 v[48:51], v[164:167], v[172:175], v[48:51]
	v_mfma_f32_16x16x32_bf16 v[36:39], v[146:149], v[188:191], v[36:39]
	v_mfma_f32_16x16x32_bf16 v[32:35], v[164:167], v[188:191], v[32:35]
	v_mfma_f32_16x16x32_bf16 v[20:23], v[146:149], v[196:199], v[20:23]
	v_mfma_f32_16x16x32_bf16 v[16:19], v[164:167], v[196:199], v[16:19]
	v_mfma_f32_16x16x32_bf16 v[4:7], v[146:149], v[204:207], v[4:7]
	v_mfma_f32_16x16x32_bf16 v[0:3], v[164:167], v[204:207], v[0:3]
	v_mfma_f32_16x16x32_bf16 v[52:55], v[160:163], v[184:187], v[52:55]
	v_mfma_f32_16x16x32_bf16 v[48:51], v[168:171], v[184:187], v[48:51]
	v_mfma_f32_16x16x32_bf16 v[36:39], v[160:163], v[192:195], v[36:39]
	v_mfma_f32_16x16x32_bf16 v[32:35], v[168:171], v[192:195], v[32:35]
	v_mfma_f32_16x16x32_bf16 v[20:23], v[160:163], v[200:203], v[20:23]
	v_mfma_f32_16x16x32_bf16 v[16:19], v[168:171], v[200:203], v[16:19]
	v_mfma_f32_16x16x32_bf16 v[4:7], v[160:163], v[226:229], v[4:7]
	v_mfma_f32_16x16x32_bf16 v[0:3], v[168:171], v[226:229], v[0:3]
	s_setprio 0
	s_add_i32 s11, s11, 2
	s_add_u32 s0, s0, 0x100
	s_addc_u32 s1, s1, 0
	s_add_u32 s9, s9, 0x100
	s_addc_u32 s10, s10, 0
	s_cmp_gt_u32 s11, 13
	s_barrier
	s_cbranch_scc0 .LBB0_29
	s_and_b64 vcc, exec, s[22:23]
	s_cbranch_vccz .LBB0_32
	s_barrier

.LBB0_51:
	s_add_u32 s12, s22, s52
	s_addc_u32 s13, s23, s53
	s_add_u32 s12, s12, 0x100
	s_addc_u32 s13, s13, 0
	s_add_u32 s14, s5, s52
	s_addc_u32 s15, s6, s53
	s_add_i32 s16, 0, 0x10000
	s_cmpk_eq_i32 s52, 0x700
	s_cselect_b32 s37, s7, s13
	s_cselect_b32 s36, s8, s12
	s_cselect_b32 s29, s9, s15
	s_cselect_b32 s28, s10, s14
	s_add_i32 s14, 0, 0x14000
	v_add_u32_e32 v158, s16, v144
	v_add_u32_e32 v162, s14, v144
	ds_read_b128 v[146:149], v158
	ds_read_b128 v[150:153], v158 offset:1024
	ds_read_b128 v[154:157], v158 offset:2048
	ds_read_b128 v[158:161], v158 offset:3072
	ds_read_b128 v[166:169], v162
	ds_read_b128 v[170:173], v162 offset:1024
	ds_read_b128 v[174:177], v162 offset:2048
	ds_read_b128 v[178:181], v162 offset:3072
	s_mov_b32 m0, s80
	v_lshl_add_u64 v[162:163], v[140:141], 0, s[52:53]
	ds_read_b128 v[182:185], v145
	ds_read_b128 v[186:189], v145 offset:1024
	ds_read_b128 v[190:193], v145 offset:2048
	ds_read_b128 v[194:197], v145 offset:3072
	ds_read_b128 v[198:201], v145 offset:4096
	ds_read_b128 v[202:205], v145 offset:5120
	ds_read_b128 v[206:209], v145 offset:6144
	ds_read_b128 v[226:229], v145 offset:7168
	global_load_lds_dwordx4 v[162:163], off
	v_lshl_add_u64 v[162:163], v[142:143], 0, s[52:53]
	s_add_i32 m0, s25, 0xe000
	s_nop 0
	global_load_lds_dwordx4 v[162:163], off
	s_waitcnt vmcnt(8)
	s_waitcnt lgkmcnt(0)
	s_barrier
	s_setprio 1
	s_waitcnt lgkmcnt(0)
	v_mfma_f32_16x16x32_bf16 v[126:129], v[146:149], v[182:185], v[126:129]
	v_mfma_f32_16x16x32_bf16 v[122:125], v[154:157], v[182:185], v[122:125]
	v_mfma_f32_16x16x32_bf16 v[110:113], v[146:149], v[190:193], v[110:113]
	v_mfma_f32_16x16x32_bf16 v[106:109], v[154:157], v[190:193], v[106:109]
	v_mfma_f32_16x16x32_bf16 v[94:97], v[146:149], v[198:201], v[94:97]
	v_mfma_f32_16x16x32_bf16 v[90:93], v[154:157], v[198:201], v[90:93]
	v_mfma_f32_16x16x32_bf16 v[78:81], v[146:149], v[206:209], v[78:81]
	v_mfma_f32_16x16x32_bf16 v[74:77], v[154:157], v[206:209], v[74:77]
	v_mfma_f32_16x16x32_bf16 v[126:129], v[150:153], v[186:189], v[126:129]
	v_mfma_f32_16x16x32_bf16 v[122:125], v[158:161], v[186:189], v[122:125]
	v_mfma_f32_16x16x32_bf16 v[110:113], v[150:153], v[194:197], v[110:113]
	v_mfma_f32_16x16x32_bf16 v[106:109], v[158:161], v[194:197], v[106:109]
	v_mfma_f32_16x16x32_bf16 v[94:97], v[150:153], v[202:205], v[94:97]
	v_mfma_f32_16x16x32_bf16 v[90:93], v[158:161], v[202:205], v[90:93]
	v_mfma_f32_16x16x32_bf16 v[78:81], v[150:153], v[226:229], v[78:81]
	v_mfma_f32_16x16x32_bf16 v[74:77], v[158:161], v[226:229], v[74:77]
	s_setprio 0
	s_setprio 1
	v_mfma_f32_16x16x32_bf16 v[118:121], v[166:169], v[182:185], v[118:121]
	v_mfma_f32_16x16x32_bf16 v[114:117], v[174:177], v[182:185], v[114:117]
	v_mfma_f32_16x16x32_bf16 v[102:105], v[166:169], v[190:193], v[102:105]
	v_mfma_f32_16x16x32_bf16 v[98:101], v[174:177], v[190:193], v[98:101]
	v_mfma_f32_16x16x32_bf16 v[86:89], v[166:169], v[198:201], v[86:89]
	v_mfma_f32_16x16x32_bf16 v[82:85], v[174:177], v[198:201], v[82:85]
	v_mfma_f32_16x16x32_bf16 v[70:73], v[166:169], v[206:209], v[70:73]
	v_mfma_f32_16x16x32_bf16 v[66:69], v[174:177], v[206:209], v[66:69]
	v_mfma_f32_16x16x32_bf16 v[118:121], v[170:173], v[186:189], v[118:121]
	v_mfma_f32_16x16x32_bf16 v[114:117], v[178:181], v[186:189], v[114:117]
	v_mfma_f32_16x16x32_bf16 v[102:105], v[170:173], v[194:197], v[102:105]
	v_mfma_f32_16x16x32_bf16 v[98:101], v[178:181], v[194:197], v[98:101]
	v_mfma_f32_16x16x32_bf16 v[86:89], v[170:173], v[202:205], v[86:89]
	v_mfma_f32_16x16x32_bf16 v[82:85], v[178:181], v[202:205], v[82:85]
	v_mfma_f32_16x16x32_bf16 v[70:73], v[170:173], v[226:229], v[70:73]
	v_mfma_f32_16x16x32_bf16 v[66:69], v[178:181], v[226:229], v[66:69]
	s_setprio 0
	s_barrier
	s_add_i32 s12, s16, s38
	v_lshl_add_u64 v[162:163], s[28:29], 0, v[64:65]
	s_mov_b32 m0, s12
	ds_read_b128 v[182:185], v145 offset:16384
	ds_read_b128 v[186:189], v145 offset:17408
	ds_read_b128 v[190:193], v145 offset:18432
	ds_read_b128 v[194:197], v145 offset:19456
	ds_read_b128 v[198:201], v145 offset:20480
	ds_read_b128 v[202:205], v145 offset:21504
	ds_read_b128 v[206:209], v145 offset:22528
	ds_read_b128 v[226:229], v145 offset:23552
	global_load_lds_dwordx4 v[162:163], off
	s_add_i32 m0, s12, 0x2000
	s_add_u32 s12, s28, 0x40000
	v_lshl_add_u64 v[210:211], s[28:29], 0, v[130:131]
	s_addc_u32 s13, s29, 0
	s_add_i32 s14, s14, s38
	global_load_lds_dwordx4 v[210:211], off
	v_lshl_add_u64 v[244:245], s[12:13], 0, v[64:65]
	s_mov_b32 m0, s14
	v_lshl_add_u64 v[212:213], s[36:37], 0, v[132:133]
	global_load_lds_dwordx4 v[244:245], off
	v_lshl_add_u64 v[244:245], s[12:13], 0, v[130:131]
	s_add_i32 m0, s14, 0x2000
	v_readlane_b32 s12, v251, 21
	global_load_lds_dwordx4 v[244:245], off
	v_lshl_add_u64 v[244:245], s[36:37], 0, v[134:135]
	s_mov_b32 m0, s25
	s_nop 0
	global_load_lds_dwordx4 v[244:245], off
	s_mov_b32 m0, s12
	s_nop 0
	global_load_lds_dwordx4 v[212:213], off
	s_waitcnt vmcnt(8)
	s_waitcnt lgkmcnt(0)
	s_barrier
	s_setprio 1
	s_waitcnt lgkmcnt(0)
	v_mfma_f32_16x16x32_bf16 v[60:63], v[146:149], v[182:185], v[60:63]
	v_mfma_f32_16x16x32_bf16 v[56:59], v[154:157], v[182:185], v[56:59]
	v_mfma_f32_16x16x32_bf16 v[44:47], v[146:149], v[190:193], v[44:47]
	v_mfma_f32_16x16x32_bf16 v[40:43], v[154:157], v[190:193], v[40:43]
	v_mfma_f32_16x16x32_bf16 v[28:31], v[146:149], v[198:201], v[28:31]
	v_mfma_f32_16x16x32_bf16 v[24:27], v[154:157], v[198:201], v[24:27]
	v_mfma_f32_16x16x32_bf16 v[12:15], v[146:149], v[206:209], v[12:15]
	v_mfma_f32_16x16x32_bf16 v[8:11], v[154:157], v[206:209], v[8:11]
	v_mfma_f32_16x16x32_bf16 v[60:63], v[150:153], v[186:189], v[60:63]
	v_mfma_f32_16x16x32_bf16 v[56:59], v[158:161], v[186:189], v[56:59]
	v_mfma_f32_16x16x32_bf16 v[44:47], v[150:153], v[194:197], v[44:47]
	v_mfma_f32_16x16x32_bf16 v[40:43], v[158:161], v[194:197], v[40:43]
	v_mfma_f32_16x16x32_bf16 v[28:31], v[150:153], v[202:205], v[28:31]
	v_mfma_f32_16x16x32_bf16 v[24:27], v[158:161], v[202:205], v[24:27]
	v_mfma_f32_16x16x32_bf16 v[12:15], v[150:153], v[226:229], v[12:15]
	v_mfma_f32_16x16x32_bf16 v[8:11], v[158:161], v[226:229], v[8:11]
	s_setprio 0
	s_setprio 1
	v_mfma_f32_16x16x32_bf16 v[52:55], v[166:169], v[182:185], v[52:55]
	v_mfma_f32_16x16x32_bf16 v[48:51], v[174:177], v[182:185], v[48:51]
	v_mfma_f32_16x16x32_bf16 v[36:39], v[166:169], v[190:193], v[36:39]
	v_mfma_f32_16x16x32_bf16 v[32:35], v[174:177], v[190:193], v[32:35]
	v_mfma_f32_16x16x32_bf16 v[20:23], v[166:169], v[198:201], v[20:23]
	v_mfma_f32_16x16x32_bf16 v[16:19], v[174:177], v[198:201], v[16:19]
	v_mfma_f32_16x16x32_bf16 v[4:7], v[166:169], v[206:209], v[4:7]
	v_mfma_f32_16x16x32_bf16 v[0:3], v[174:177], v[206:209], v[0:3]
	v_mfma_f32_16x16x32_bf16 v[52:55], v[170:173], v[186:189], v[52:55]
	v_mfma_f32_16x16x32_bf16 v[48:51], v[178:181], v[186:189], v[48:51]
	v_mfma_f32_16x16x32_bf16 v[36:39], v[170:173], v[194:197], v[36:39]
	v_mfma_f32_16x16x32_bf16 v[32:35], v[178:181], v[194:197], v[32:35]
	v_mfma_f32_16x16x32_bf16 v[20:23], v[170:173], v[202:205], v[20:23]
	v_mfma_f32_16x16x32_bf16 v[16:19], v[178:181], v[202:205], v[16:19]
	v_mfma_f32_16x16x32_bf16 v[4:7], v[170:173], v[226:229], v[4:7]
	v_mfma_f32_16x16x32_bf16 v[0:3], v[178:181], v[226:229], v[0:3]
	s_setprio 0
	s_barrier
	s_add_i32 s14, 0, 0x18000
	s_add_i32 s15, 0, 0x1c000
	v_add_u32_e32 v158, s14, v144
	v_add_u32_e32 v178, s15, v144
	ds_read_b128 v[146:149], v158
	ds_read_b128 v[150:153], v158 offset:1024
	ds_read_b128 v[154:157], v158 offset:2048
	ds_read_b128 v[158:161], v158 offset:3072
	ds_read_b128 v[166:169], v178
	ds_read_b128 v[170:173], v178 offset:1024
	ds_read_b128 v[174:177], v178 offset:2048
	ds_read_b128 v[178:181], v178 offset:3072
	s_add_u32 s12, s36, 0x40000
	s_addc_u32 s13, s37, 0
	s_mov_b32 m0, s75
	v_lshl_add_u64 v[218:219], s[12:13], 0, v[134:135]
	ds_read_b128 v[182:185], v145 offset:32768
	ds_read_b128 v[186:189], v145 offset:33792
	ds_read_b128 v[190:193], v145 offset:34816
	ds_read_b128 v[194:197], v145 offset:35840
	ds_read_b128 v[198:201], v145 offset:36864
	ds_read_b128 v[202:205], v145 offset:37888
	ds_read_b128 v[206:209], v145 offset:38912
	ds_read_b128 v[226:229], v145 offset:39936
	global_load_lds_dwordx4 v[218:219], off
	v_lshl_add_u64 v[218:219], s[12:13], 0, v[132:133]
	s_mov_b32 m0, s74
	s_nop 0
	global_load_lds_dwordx4 v[218:219], off
	s_waitcnt vmcnt(8)
	s_waitcnt lgkmcnt(0)
	s_barrier
	s_setprio 1
	s_waitcnt lgkmcnt(0)
	v_mfma_f32_16x16x32_bf16 v[126:129], v[146:149], v[182:185], v[126:129]
	v_mfma_f32_16x16x32_bf16 v[122:125], v[154:157], v[182:185], v[122:125]
	v_mfma_f32_16x16x32_bf16 v[110:113], v[146:149], v[190:193], v[110:113]
	v_mfma_f32_16x16x32_bf16 v[106:109], v[154:157], v[190:193], v[106:109]
	v_mfma_f32_16x16x32_bf16 v[94:97], v[146:149], v[198:201], v[94:97]
	v_mfma_f32_16x16x32_bf16 v[90:93], v[154:157], v[198:201], v[90:93]
	v_mfma_f32_16x16x32_bf16 v[78:81], v[146:149], v[206:209], v[78:81]
	v_mfma_f32_16x16x32_bf16 v[74:77], v[154:157], v[206:209], v[74:77]
	v_mfma_f32_16x16x32_bf16 v[126:129], v[150:153], v[186:189], v[126:129]
	v_mfma_f32_16x16x32_bf16 v[122:125], v[158:161], v[186:189], v[122:125]
	v_mfma_f32_16x16x32_bf16 v[110:113], v[150:153], v[194:197], v[110:113]
	v_mfma_f32_16x16x32_bf16 v[106:109], v[158:161], v[194:197], v[106:109]
	v_mfma_f32_16x16x32_bf16 v[94:97], v[150:153], v[202:205], v[94:97]
	v_mfma_f32_16x16x32_bf16 v[90:93], v[158:161], v[202:205], v[90:93]
	v_mfma_f32_16x16x32_bf16 v[78:81], v[150:153], v[226:229], v[78:81]
	v_mfma_f32_16x16x32_bf16 v[74:77], v[158:161], v[226:229], v[74:77]
	s_setprio 0
	s_setprio 1
	v_mfma_f32_16x16x32_bf16 v[118:121], v[166:169], v[182:185], v[118:121]
	v_mfma_f32_16x16x32_bf16 v[114:117], v[174:177], v[182:185], v[114:117]
	v_mfma_f32_16x16x32_bf16 v[102:105], v[166:169], v[190:193], v[102:105]
	v_mfma_f32_16x16x32_bf16 v[98:101], v[174:177], v[190:193], v[98:101]
	v_mfma_f32_16x16x32_bf16 v[86:89], v[166:169], v[198:201], v[86:89]
	v_mfma_f32_16x16x32_bf16 v[82:85], v[174:177], v[198:201], v[82:85]
	v_mfma_f32_16x16x32_bf16 v[70:73], v[166:169], v[206:209], v[70:73]
	v_mfma_f32_16x16x32_bf16 v[66:69], v[174:177], v[206:209], v[66:69]
	v_mfma_f32_16x16x32_bf16 v[118:121], v[170:173], v[186:189], v[118:121]
	v_mfma_f32_16x16x32_bf16 v[114:117], v[178:181], v[186:189], v[114:117]
	v_mfma_f32_16x16x32_bf16 v[102:105], v[170:173], v[194:197], v[102:105]
	v_mfma_f32_16x16x32_bf16 v[98:101], v[178:181], v[194:197], v[98:101]
	v_mfma_f32_16x16x32_bf16 v[86:89], v[170:173], v[202:205], v[86:89]
	v_mfma_f32_16x16x32_bf16 v[82:85], v[178:181], v[202:205], v[82:85]
	v_mfma_f32_16x16x32_bf16 v[70:73], v[170:173], v[226:229], v[70:73]
	v_mfma_f32_16x16x32_bf16 v[66:69], v[178:181], v[226:229], v[66:69]
	s_setprio 0
	s_barrier
	s_add_i32 s12, s14, s38
	v_lshl_add_u64 v[162:163], v[162:163], 0, s[40:41]
	s_mov_b32 m0, s12
	ds_read_b128 v[182:185], v145 offset:49152
	ds_read_b128 v[186:189], v145 offset:50176
	ds_read_b128 v[190:193], v145 offset:51200
	ds_read_b128 v[194:197], v145 offset:52224
	ds_read_b128 v[198:201], v145 offset:53248
	ds_read_b128 v[202:205], v145 offset:54272
	ds_read_b128 v[206:209], v145 offset:55296
	ds_read_b128 v[226:229], v145 offset:56320
	global_load_lds_dwordx4 v[162:163], off
	s_add_i32 m0, s12, 0x2000
	s_add_u32 s12, s28, 0x40080
	v_lshl_add_u64 v[162:163], v[210:211], 0, s[40:41]
	s_addc_u32 s13, s29, 0
	s_add_i32 s14, s15, s38
	global_load_lds_dwordx4 v[162:163], off
	v_lshl_add_u64 v[162:163], s[12:13], 0, v[64:65]
	s_mov_b32 m0, s14
	s_nop 0
	global_load_lds_dwordx4 v[162:163], off
	v_lshl_add_u64 v[162:163], s[12:13], 0, v[130:131]
	s_add_i32 m0, s14, 0x2000
	s_nop 0
	global_load_lds_dwordx4 v[162:163], off
	v_lshl_add_u64 v[162:163], v[244:245], 0, s[40:41]
	s_mov_b32 m0, s92
	s_nop 0
	global_load_lds_dwordx4 v[162:163], off
	v_lshl_add_u64 v[162:163], v[212:213], 0, s[40:41]
	s_mov_b32 m0, s78
	s_nop 0
	global_load_lds_dwordx4 v[162:163], off
	s_waitcnt vmcnt(8)
	s_waitcnt lgkmcnt(0)
	s_barrier
	s_setprio 1
	s_waitcnt lgkmcnt(0)
	v_mfma_f32_16x16x32_bf16 v[60:63], v[146:149], v[182:185], v[60:63]
	v_mfma_f32_16x16x32_bf16 v[56:59], v[154:157], v[182:185], v[56:59]
	v_mfma_f32_16x16x32_bf16 v[44:47], v[146:149], v[190:193], v[44:47]
	v_mfma_f32_16x16x32_bf16 v[40:43], v[154:157], v[190:193], v[40:43]
	v_mfma_f32_16x16x32_bf16 v[28:31], v[146:149], v[198:201], v[28:31]
	v_mfma_f32_16x16x32_bf16 v[24:27], v[154:157], v[198:201], v[24:27]
	v_mfma_f32_16x16x32_bf16 v[12:15], v[146:149], v[206:209], v[12:15]
	v_mfma_f32_16x16x32_bf16 v[8:11], v[154:157], v[206:209], v[8:11]
	v_mfma_f32_16x16x32_bf16 v[60:63], v[150:153], v[186:189], v[60:63]
	v_mfma_f32_16x16x32_bf16 v[56:59], v[158:161], v[186:189], v[56:59]
	v_mfma_f32_16x16x32_bf16 v[44:47], v[150:153], v[194:197], v[44:47]
	v_mfma_f32_16x16x32_bf16 v[40:43], v[158:161], v[194:197], v[40:43]
	v_mfma_f32_16x16x32_bf16 v[28:31], v[150:153], v[202:205], v[28:31]
	v_mfma_f32_16x16x32_bf16 v[24:27], v[158:161], v[202:205], v[24:27]
	v_mfma_f32_16x16x32_bf16 v[12:15], v[150:153], v[226:229], v[12:15]
	v_mfma_f32_16x16x32_bf16 v[8:11], v[158:161], v[226:229], v[8:11]
	s_setprio 0
	s_setprio 1
	v_mfma_f32_16x16x32_bf16 v[52:55], v[166:169], v[182:185], v[52:55]
	v_mfma_f32_16x16x32_bf16 v[48:51], v[174:177], v[182:185], v[48:51]
	v_mfma_f32_16x16x32_bf16 v[36:39], v[166:169], v[190:193], v[36:39]
	v_mfma_f32_16x16x32_bf16 v[32:35], v[174:177], v[190:193], v[32:35]
	v_mfma_f32_16x16x32_bf16 v[20:23], v[166:169], v[198:201], v[20:23]
	v_mfma_f32_16x16x32_bf16 v[16:19], v[174:177], v[198:201], v[16:19]
	v_mfma_f32_16x16x32_bf16 v[4:7], v[166:169], v[206:209], v[4:7]
	v_mfma_f32_16x16x32_bf16 v[0:3], v[174:177], v[206:209], v[0:3]
	v_mfma_f32_16x16x32_bf16 v[52:55], v[170:173], v[186:189], v[52:55]
	v_mfma_f32_16x16x32_bf16 v[48:51], v[178:181], v[186:189], v[48:51]
	v_mfma_f32_16x16x32_bf16 v[36:39], v[170:173], v[194:197], v[36:39]
	v_mfma_f32_16x16x32_bf16 v[32:35], v[178:181], v[194:197], v[32:35]
	v_mfma_f32_16x16x32_bf16 v[20:23], v[170:173], v[202:205], v[20:23]
	v_mfma_f32_16x16x32_bf16 v[16:19], v[178:181], v[202:205], v[16:19]
	v_mfma_f32_16x16x32_bf16 v[4:7], v[170:173], v[226:229], v[4:7]
	v_mfma_f32_16x16x32_bf16 v[0:3], v[178:181], v[226:229], v[0:3]
	s_setprio 0
	s_add_i32 s11, s11, 2
	s_add_u32 s52, s52, 0x100
	s_addc_u32 s53, s53, 0
	s_cmp_gt_u32 s11, 13
	s_barrier
	s_cbranch_scc0 .LBB0_51
	s_add_u32 s28, s5, 0xffffff00
	s_addc_u32 s29, s6, -1
	s_andn2_b64 vcc, exec, s[0:1]
	s_cbranch_vccnz .LBB0_54
	v_mov_b32_e32 v0, 0
	s_mov_b32 s2, s44
	s_mov_b32 s54, s46
	s_mov_b64 s[22:23], s[50:51]
	s_mov_b32 s56, s4
	v_mov_b32_e32 v1, v0
	v_mov_b32_e32 v2, v0
	v_mov_b32_e32 v3, v0
	v_mov_b32_e32 v4, v0
	v_mov_b32_e32 v5, v0
	v_mov_b32_e32 v6, v0
	v_mov_b32_e32 v7, v0
	v_mov_b32_e32 v16, v0
	v_mov_b32_e32 v17, v0
	v_mov_b32_e32 v18, v0
	v_mov_b32_e32 v19, v0
	v_mov_b32_e32 v20, v0
	v_mov_b32_e32 v21, v0
	v_mov_b32_e32 v22, v0
	v_mov_b32_e32 v23, v0
	v_mov_b32_e32 v32, v0
	v_mov_b32_e32 v33, v0
	v_mov_b32_e32 v34, v0
	v_mov_b32_e32 v35, v0
	v_mov_b32_e32 v36, v0
	v_mov_b32_e32 v37, v0
	v_mov_b32_e32 v38, v0
	v_mov_b32_e32 v39, v0
	v_mov_b32_e32 v48, v0
	v_mov_b32_e32 v49, v0
	v_mov_b32_e32 v50, v0
	v_mov_b32_e32 v51, v0
	v_mov_b32_e32 v52, v0
	v_mov_b32_e32 v53, v0
	v_mov_b32_e32 v54, v0
	v_mov_b32_e32 v55, v0
	v_mov_b32_e32 v8, v0
	v_mov_b32_e32 v9, v0
	v_mov_b32_e32 v10, v0
	v_mov_b32_e32 v11, v0
	v_mov_b32_e32 v12, v0
	v_mov_b32_e32 v13, v0
	v_mov_b32_e32 v14, v0
	v_mov_b32_e32 v15, v0
	v_mov_b32_e32 v24, v0
	v_mov_b32_e32 v25, v0
	v_mov_b32_e32 v26, v0
	v_mov_b32_e32 v27, v0
	v_mov_b32_e32 v28, v0
	v_mov_b32_e32 v29, v0
	v_mov_b32_e32 v30, v0
	v_mov_b32_e32 v31, v0
	v_mov_b32_e32 v40, v0
	v_mov_b32_e32 v41, v0
	v_mov_b32_e32 v42, v0
	v_mov_b32_e32 v43, v0
	v_mov_b32_e32 v44, v0
	v_mov_b32_e32 v45, v0
	v_mov_b32_e32 v46, v0
	v_mov_b32_e32 v47, v0
	v_mov_b32_e32 v56, v0
	v_mov_b32_e32 v57, v0
	v_mov_b32_e32 v58, v0
	v_mov_b32_e32 v59, v0
	v_mov_b32_e32 v60, v0
	v_mov_b32_e32 v61, v0
	v_mov_b32_e32 v62, v0
	v_mov_b32_e32 v63, v0
	v_mov_b32_e32 v66, v0
	v_mov_b32_e32 v67, v0
	v_mov_b32_e32 v68, v0
	v_mov_b32_e32 v69, v0
	v_mov_b32_e32 v70, v0
	v_mov_b32_e32 v71, v0
	v_mov_b32_e32 v72, v0
	v_mov_b32_e32 v73, v0
	v_mov_b32_e32 v82, v0
	v_mov_b32_e32 v83, v0
	v_mov_b32_e32 v84, v0
	v_mov_b32_e32 v85, v0
	v_mov_b32_e32 v86, v0
	v_mov_b32_e32 v87, v0
	v_mov_b32_e32 v88, v0
	v_mov_b32_e32 v89, v0
	v_mov_b32_e32 v98, v0
	v_mov_b32_e32 v99, v0
	v_mov_b32_e32 v100, v0
	v_mov_b32_e32 v101, v0
	v_mov_b32_e32 v102, v0
	v_mov_b32_e32 v103, v0
	v_mov_b32_e32 v104, v0
	v_mov_b32_e32 v105, v0
	v_mov_b32_e32 v114, v0
	v_mov_b32_e32 v115, v0
	v_mov_b32_e32 v116, v0
	v_mov_b32_e32 v117, v0
	v_mov_b32_e32 v118, v0
	v_mov_b32_e32 v119, v0
	v_mov_b32_e32 v120, v0
	v_mov_b32_e32 v121, v0
	v_mov_b32_e32 v74, v0
	v_mov_b32_e32 v75, v0
	v_mov_b32_e32 v76, v0
	v_mov_b32_e32 v77, v0
	v_mov_b32_e32 v78, v0
	v_mov_b32_e32 v79, v0
	v_mov_b32_e32 v80, v0
	v_mov_b32_e32 v81, v0
	v_mov_b32_e32 v90, v0
	v_mov_b32_e32 v91, v0
	v_mov_b32_e32 v92, v0
	v_mov_b32_e32 v93, v0
	v_mov_b32_e32 v94, v0
	v_mov_b32_e32 v95, v0
	v_mov_b32_e32 v96, v0
	v_mov_b32_e32 v97, v0
	v_mov_b32_e32 v106, v0
	v_mov_b32_e32 v107, v0
	v_mov_b32_e32 v108, v0
	v_mov_b32_e32 v109, v0
	v_mov_b32_e32 v110, v0
	v_mov_b32_e32 v111, v0
	v_mov_b32_e32 v112, v0
	v_mov_b32_e32 v113, v0
	v_mov_b32_e32 v122, v0
	v_mov_b32_e32 v123, v0
	v_mov_b32_e32 v124, v0
	v_mov_b32_e32 v125, v0
	v_mov_b32_e32 v126, v0
	v_mov_b32_e32 v127, v0
	v_mov_b32_e32 v128, v0
	v_mov_b32_e32 v129, v0
	s_andn2_b64 vcc, exec, s[42:43]
	s_cbranch_vccnz .LBB0_55
	s_branch .LBB0_56

.LBB0_572:
	s_add_u32 s12, s22, s52
	s_addc_u32 s13, s23, s53
	s_add_u32 s12, s12, 0x100
	s_addc_u32 s13, s13, 0
	s_add_u32 s14, s5, s52
	s_addc_u32 s15, s6, s53
	s_add_i32 s16, 0, 0x10000
	s_cmpk_eq_i32 s52, 0x1f00
	s_cselect_b32 s37, s7, s13
	s_cselect_b32 s36, s8, s12
	v_add_u32_e32 v146, s16, v104
	s_cselect_b32 s29, s9, s15
	s_cselect_b32 s28, s10, s14
	s_add_i32 s14, 0, 0x14000
	ds_read_b128 v[150:153], v146
	ds_read_b128 v[154:157], v146 offset:1024
	ds_read_b128 v[158:161], v146 offset:2048
	ds_read_b128 v[162:165], v146 offset:3072
	v_add_u32_e32 v146, s14, v104
	ds_read_b128 v[166:169], v146
	ds_read_b128 v[170:173], v146 offset:1024
	ds_read_b128 v[174:177], v146 offset:2048
	ds_read_b128 v[178:181], v146 offset:3072
	s_mov_b32 m0, s80
	v_lshl_add_u64 v[146:147], v[100:101], 0, s[52:53]
	ds_read_b128 v[182:185], v105
	ds_read_b128 v[186:189], v105 offset:1024
	ds_read_b128 v[190:193], v105 offset:2048
	ds_read_b128 v[194:197], v105 offset:3072
	ds_read_b128 v[198:201], v105 offset:4096
	ds_read_b128 v[202:205], v105 offset:5120
	ds_read_b128 v[206:209], v105 offset:6144
	ds_read_b128 v[226:229], v105 offset:7168
	global_load_lds_dwordx4 v[146:147], off
	v_lshl_add_u64 v[146:147], v[102:103], 0, s[52:53]
	s_add_i32 m0, s25, 0xe000
	s_nop 0
	global_load_lds_dwordx4 v[146:147], off
	s_waitcnt vmcnt(8)
	s_waitcnt lgkmcnt(0)
	s_barrier
	s_setprio 1
	s_waitcnt lgkmcnt(0)
	v_mfma_f32_16x16x32_bf16 v[134:137], v[150:153], v[182:185], v[134:137]
	v_mfma_f32_16x16x32_bf16 v[142:145], v[158:161], v[182:185], v[142:145]
	v_mfma_f32_16x16x32_bf16 v[126:129], v[150:153], v[190:193], v[126:129]
	v_mfma_f32_16x16x32_bf16 v[122:125], v[158:161], v[190:193], v[122:125]
	v_mfma_f32_16x16x32_bf16 v[110:113], v[150:153], v[198:201], v[110:113]
	v_mfma_f32_16x16x32_bf16 v[106:109], v[158:161], v[198:201], v[106:109]
	v_mfma_f32_16x16x32_bf16 v[78:81], v[150:153], v[206:209], v[78:81]
	v_mfma_f32_16x16x32_bf16 v[74:77], v[158:161], v[206:209], v[74:77]
	v_mfma_f32_16x16x32_bf16 v[134:137], v[154:157], v[186:189], v[134:137]
	v_mfma_f32_16x16x32_bf16 v[142:145], v[162:165], v[186:189], v[142:145]
	v_mfma_f32_16x16x32_bf16 v[126:129], v[154:157], v[194:197], v[126:129]
	v_mfma_f32_16x16x32_bf16 v[122:125], v[162:165], v[194:197], v[122:125]
	v_mfma_f32_16x16x32_bf16 v[110:113], v[154:157], v[202:205], v[110:113]
	v_mfma_f32_16x16x32_bf16 v[106:109], v[162:165], v[202:205], v[106:109]
	v_mfma_f32_16x16x32_bf16 v[78:81], v[154:157], v[226:229], v[78:81]
	v_mfma_f32_16x16x32_bf16 v[74:77], v[162:165], v[226:229], v[74:77]
	s_setprio 0
	s_setprio 1
	v_mfma_f32_16x16x32_bf16 v[138:141], v[166:169], v[182:185], v[138:141]
	v_mfma_f32_16x16x32_bf16 v[130:133], v[174:177], v[182:185], v[130:133]
	v_mfma_f32_16x16x32_bf16 v[118:121], v[166:169], v[190:193], v[118:121]
	v_mfma_f32_16x16x32_bf16 v[114:117], v[174:177], v[190:193], v[114:117]
	v_mfma_f32_16x16x32_bf16 v[94:97], v[166:169], v[198:201], v[94:97]
	v_mfma_f32_16x16x32_bf16 v[86:89], v[174:177], v[198:201], v[86:89]
	v_mfma_f32_16x16x32_bf16 v[70:73], v[166:169], v[206:209], v[70:73]
	v_mfma_f32_16x16x32_bf16 v[66:69], v[174:177], v[206:209], v[66:69]
	v_mfma_f32_16x16x32_bf16 v[138:141], v[170:173], v[186:189], v[138:141]
	v_mfma_f32_16x16x32_bf16 v[130:133], v[178:181], v[186:189], v[130:133]
	v_mfma_f32_16x16x32_bf16 v[118:121], v[170:173], v[194:197], v[118:121]
	v_mfma_f32_16x16x32_bf16 v[114:117], v[178:181], v[194:197], v[114:117]
	v_mfma_f32_16x16x32_bf16 v[94:97], v[170:173], v[202:205], v[94:97]
	v_mfma_f32_16x16x32_bf16 v[86:89], v[178:181], v[202:205], v[86:89]
	v_mfma_f32_16x16x32_bf16 v[70:73], v[170:173], v[226:229], v[70:73]
	v_mfma_f32_16x16x32_bf16 v[66:69], v[178:181], v[226:229], v[66:69]
	s_setprio 0
	s_barrier
	s_add_i32 s12, s16, s38
	v_lshl_add_u64 v[146:147], s[28:29], 0, v[64:65]
	s_mov_b32 m0, s12
	ds_read_b128 v[182:185], v105 offset:16384
	ds_read_b128 v[186:189], v105 offset:17408
	ds_read_b128 v[190:193], v105 offset:18432
	ds_read_b128 v[194:197], v105 offset:19456
	ds_read_b128 v[198:201], v105 offset:20480
	ds_read_b128 v[202:205], v105 offset:21504
	ds_read_b128 v[206:209], v105 offset:22528
	ds_read_b128 v[226:229], v105 offset:23552
	global_load_lds_dwordx4 v[146:147], off
	s_add_i32 m0, s12, 0x2000
	s_add_u32 s12, s28, 0x100000
	v_lshl_add_u64 v[210:211], s[28:29], 0, v[82:83]
	s_addc_u32 s13, s29, 0
	s_add_i32 s14, s14, s38
	global_load_lds_dwordx4 v[210:211], off
	v_lshl_add_u64 v[212:213], s[12:13], 0, v[64:65]
	s_mov_b32 m0, s14
	v_lshl_add_u64 v[218:219], s[36:37], 0, v[84:85]
	global_load_lds_dwordx4 v[212:213], off
	v_lshl_add_u64 v[212:213], s[12:13], 0, v[82:83]
	s_add_i32 m0, s14, 0x2000
	v_readlane_b32 s12, v251, 21
	global_load_lds_dwordx4 v[212:213], off
	v_lshl_add_u64 v[212:213], s[36:37], 0, v[90:91]
	s_mov_b32 m0, s25
	s_nop 0
	global_load_lds_dwordx4 v[212:213], off
	s_mov_b32 m0, s12
	s_nop 0
	global_load_lds_dwordx4 v[218:219], off
	s_waitcnt vmcnt(8)
	s_waitcnt lgkmcnt(0)
	s_barrier
	s_setprio 1
	s_waitcnt lgkmcnt(0)
	v_mfma_f32_16x16x32_bf16 v[60:63], v[150:153], v[182:185], v[60:63]
	v_mfma_f32_16x16x32_bf16 v[56:59], v[158:161], v[182:185], v[56:59]
	v_mfma_f32_16x16x32_bf16 v[44:47], v[150:153], v[190:193], v[44:47]
	v_mfma_f32_16x16x32_bf16 v[40:43], v[158:161], v[190:193], v[40:43]
	v_mfma_f32_16x16x32_bf16 v[28:31], v[150:153], v[198:201], v[28:31]
	v_mfma_f32_16x16x32_bf16 v[24:27], v[158:161], v[198:201], v[24:27]
	v_mfma_f32_16x16x32_bf16 v[12:15], v[150:153], v[206:209], v[12:15]
	v_mfma_f32_16x16x32_bf16 v[8:11], v[158:161], v[206:209], v[8:11]
	v_mfma_f32_16x16x32_bf16 v[60:63], v[154:157], v[186:189], v[60:63]
	v_mfma_f32_16x16x32_bf16 v[56:59], v[162:165], v[186:189], v[56:59]
	v_mfma_f32_16x16x32_bf16 v[44:47], v[154:157], v[194:197], v[44:47]
	v_mfma_f32_16x16x32_bf16 v[40:43], v[162:165], v[194:197], v[40:43]
	v_mfma_f32_16x16x32_bf16 v[28:31], v[154:157], v[202:205], v[28:31]
	v_mfma_f32_16x16x32_bf16 v[24:27], v[162:165], v[202:205], v[24:27]
	v_mfma_f32_16x16x32_bf16 v[12:15], v[154:157], v[226:229], v[12:15]
	v_mfma_f32_16x16x32_bf16 v[8:11], v[162:165], v[226:229], v[8:11]
	s_setprio 0
	s_setprio 1
	v_mfma_f32_16x16x32_bf16 v[52:55], v[166:169], v[182:185], v[52:55]
	v_mfma_f32_16x16x32_bf16 v[48:51], v[174:177], v[182:185], v[48:51]
	v_mfma_f32_16x16x32_bf16 v[36:39], v[166:169], v[190:193], v[36:39]
	v_mfma_f32_16x16x32_bf16 v[32:35], v[174:177], v[190:193], v[32:35]
	v_mfma_f32_16x16x32_bf16 v[20:23], v[166:169], v[198:201], v[20:23]
	v_mfma_f32_16x16x32_bf16 v[16:19], v[174:177], v[198:201], v[16:19]
	v_mfma_f32_16x16x32_bf16 v[4:7], v[166:169], v[206:209], v[4:7]
	v_mfma_f32_16x16x32_bf16 v[0:3], v[174:177], v[206:209], v[0:3]
	v_mfma_f32_16x16x32_bf16 v[52:55], v[170:173], v[186:189], v[52:55]
	v_mfma_f32_16x16x32_bf16 v[48:51], v[178:181], v[186:189], v[48:51]
	v_mfma_f32_16x16x32_bf16 v[36:39], v[170:173], v[194:197], v[36:39]
	v_mfma_f32_16x16x32_bf16 v[32:35], v[178:181], v[194:197], v[32:35]
	v_mfma_f32_16x16x32_bf16 v[20:23], v[170:173], v[202:205], v[20:23]
	v_mfma_f32_16x16x32_bf16 v[16:19], v[178:181], v[202:205], v[16:19]
	v_mfma_f32_16x16x32_bf16 v[4:7], v[170:173], v[226:229], v[4:7]
	v_mfma_f32_16x16x32_bf16 v[0:3], v[178:181], v[226:229], v[0:3]
	s_setprio 0
	s_barrier
	s_add_i32 s14, 0, 0x18000
	s_add_i32 s15, 0, 0x1c000
	v_add_u32_e32 v162, s14, v104
	v_add_u32_e32 v178, s15, v104
	ds_read_b128 v[150:153], v162
	ds_read_b128 v[154:157], v162 offset:1024
	ds_read_b128 v[158:161], v162 offset:2048
	ds_read_b128 v[162:165], v162 offset:3072
	ds_read_b128 v[166:169], v178
	ds_read_b128 v[170:173], v178 offset:1024
	ds_read_b128 v[174:177], v178 offset:2048
	ds_read_b128 v[178:181], v178 offset:3072
	s_add_u32 s12, s36, 0x100000
	s_addc_u32 s13, s37, 0
	s_mov_b32 m0, s75
	v_lshl_add_u64 v[230:231], s[12:13], 0, v[90:91]
	ds_read_b128 v[182:185], v105 offset:32768
	ds_read_b128 v[186:189], v105 offset:33792
	ds_read_b128 v[190:193], v105 offset:34816
	ds_read_b128 v[194:197], v105 offset:35840
	ds_read_b128 v[198:201], v105 offset:36864
	ds_read_b128 v[202:205], v105 offset:37888
	ds_read_b128 v[206:209], v105 offset:38912
	ds_read_b128 v[226:229], v105 offset:39936
	global_load_lds_dwordx4 v[230:231], off
	v_lshl_add_u64 v[230:231], s[12:13], 0, v[84:85]
	s_mov_b32 m0, s74
	s_nop 0
	global_load_lds_dwordx4 v[230:231], off
	s_waitcnt vmcnt(8)
	s_waitcnt lgkmcnt(0)
	s_barrier
	s_setprio 1
	s_waitcnt lgkmcnt(0)
	v_mfma_f32_16x16x32_bf16 v[134:137], v[150:153], v[182:185], v[134:137]
	v_mfma_f32_16x16x32_bf16 v[142:145], v[158:161], v[182:185], v[142:145]
	v_mfma_f32_16x16x32_bf16 v[126:129], v[150:153], v[190:193], v[126:129]
	v_mfma_f32_16x16x32_bf16 v[122:125], v[158:161], v[190:193], v[122:125]
	v_mfma_f32_16x16x32_bf16 v[110:113], v[150:153], v[198:201], v[110:113]
	v_mfma_f32_16x16x32_bf16 v[106:109], v[158:161], v[198:201], v[106:109]
	v_mfma_f32_16x16x32_bf16 v[78:81], v[150:153], v[206:209], v[78:81]
	v_mfma_f32_16x16x32_bf16 v[74:77], v[158:161], v[206:209], v[74:77]
	v_mfma_f32_16x16x32_bf16 v[134:137], v[154:157], v[186:189], v[134:137]
	v_mfma_f32_16x16x32_bf16 v[142:145], v[162:165], v[186:189], v[142:145]
	v_mfma_f32_16x16x32_bf16 v[126:129], v[154:157], v[194:197], v[126:129]
	v_mfma_f32_16x16x32_bf16 v[122:125], v[162:165], v[194:197], v[122:125]
	v_mfma_f32_16x16x32_bf16 v[110:113], v[154:157], v[202:205], v[110:113]
	v_mfma_f32_16x16x32_bf16 v[106:109], v[162:165], v[202:205], v[106:109]
	v_mfma_f32_16x16x32_bf16 v[78:81], v[154:157], v[226:229], v[78:81]
	v_mfma_f32_16x16x32_bf16 v[74:77], v[162:165], v[226:229], v[74:77]
	s_setprio 0
	s_setprio 1
	v_mfma_f32_16x16x32_bf16 v[138:141], v[166:169], v[182:185], v[138:141]
	v_mfma_f32_16x16x32_bf16 v[130:133], v[174:177], v[182:185], v[130:133]
	v_mfma_f32_16x16x32_bf16 v[118:121], v[166:169], v[190:193], v[118:121]
	v_mfma_f32_16x16x32_bf16 v[114:117], v[174:177], v[190:193], v[114:117]
	v_mfma_f32_16x16x32_bf16 v[94:97], v[166:169], v[198:201], v[94:97]
	v_mfma_f32_16x16x32_bf16 v[86:89], v[174:177], v[198:201], v[86:89]
	v_mfma_f32_16x16x32_bf16 v[70:73], v[166:169], v[206:209], v[70:73]
	v_mfma_f32_16x16x32_bf16 v[66:69], v[174:177], v[206:209], v[66:69]
	v_mfma_f32_16x16x32_bf16 v[138:141], v[170:173], v[186:189], v[138:141]
	v_mfma_f32_16x16x32_bf16 v[130:133], v[178:181], v[186:189], v[130:133]
	v_mfma_f32_16x16x32_bf16 v[118:121], v[170:173], v[194:197], v[118:121]
	v_mfma_f32_16x16x32_bf16 v[114:117], v[178:181], v[194:197], v[114:117]
	v_mfma_f32_16x16x32_bf16 v[94:97], v[170:173], v[202:205], v[94:97]
	v_mfma_f32_16x16x32_bf16 v[86:89], v[178:181], v[202:205], v[86:89]
	v_mfma_f32_16x16x32_bf16 v[70:73], v[170:173], v[226:229], v[70:73]
	v_mfma_f32_16x16x32_bf16 v[66:69], v[178:181], v[226:229], v[66:69]
	s_setprio 0
	s_barrier
	s_add_i32 s12, s14, s38
	v_lshl_add_u64 v[146:147], v[146:147], 0, s[18:19]
	s_mov_b32 m0, s12
	ds_read_b128 v[182:185], v105 offset:49152
	ds_read_b128 v[186:189], v105 offset:50176
	ds_read_b128 v[190:193], v105 offset:51200
	ds_read_b128 v[194:197], v105 offset:52224
	ds_read_b128 v[198:201], v105 offset:53248
	ds_read_b128 v[202:205], v105 offset:54272
	ds_read_b128 v[206:209], v105 offset:55296
	ds_read_b128 v[226:229], v105 offset:56320
	global_load_lds_dwordx4 v[146:147], off
	s_add_i32 m0, s12, 0x2000
	s_add_u32 s12, s28, 0x100080
	v_lshl_add_u64 v[146:147], v[210:211], 0, s[18:19]
	s_addc_u32 s13, s29, 0
	s_add_i32 s14, s15, s38
	global_load_lds_dwordx4 v[146:147], off
	v_lshl_add_u64 v[146:147], s[12:13], 0, v[64:65]
	s_mov_b32 m0, s14
	s_nop 0
	global_load_lds_dwordx4 v[146:147], off
	v_lshl_add_u64 v[146:147], s[12:13], 0, v[82:83]
	s_add_i32 m0, s14, 0x2000
	s_nop 0
	global_load_lds_dwordx4 v[146:147], off
	v_lshl_add_u64 v[146:147], v[212:213], 0, s[18:19]
	s_mov_b32 m0, s92
	s_nop 0
	global_load_lds_dwordx4 v[146:147], off
	v_lshl_add_u64 v[146:147], v[218:219], 0, s[18:19]
	s_mov_b32 m0, s78
	s_nop 0
	global_load_lds_dwordx4 v[146:147], off
	s_waitcnt vmcnt(8)
	s_waitcnt lgkmcnt(0)
	s_barrier
	s_setprio 1
	s_waitcnt lgkmcnt(0)
	v_mfma_f32_16x16x32_bf16 v[60:63], v[150:153], v[182:185], v[60:63]
	v_mfma_f32_16x16x32_bf16 v[56:59], v[158:161], v[182:185], v[56:59]
	v_mfma_f32_16x16x32_bf16 v[44:47], v[150:153], v[190:193], v[44:47]
	v_mfma_f32_16x16x32_bf16 v[40:43], v[158:161], v[190:193], v[40:43]
	v_mfma_f32_16x16x32_bf16 v[28:31], v[150:153], v[198:201], v[28:31]
	v_mfma_f32_16x16x32_bf16 v[24:27], v[158:161], v[198:201], v[24:27]
	v_mfma_f32_16x16x32_bf16 v[12:15], v[150:153], v[206:209], v[12:15]
	v_mfma_f32_16x16x32_bf16 v[8:11], v[158:161], v[206:209], v[8:11]
	v_mfma_f32_16x16x32_bf16 v[60:63], v[154:157], v[186:189], v[60:63]
	v_mfma_f32_16x16x32_bf16 v[56:59], v[162:165], v[186:189], v[56:59]
	v_mfma_f32_16x16x32_bf16 v[44:47], v[154:157], v[194:197], v[44:47]
	v_mfma_f32_16x16x32_bf16 v[40:43], v[162:165], v[194:197], v[40:43]
	v_mfma_f32_16x16x32_bf16 v[28:31], v[154:157], v[202:205], v[28:31]
	v_mfma_f32_16x16x32_bf16 v[24:27], v[162:165], v[202:205], v[24:27]
	v_mfma_f32_16x16x32_bf16 v[12:15], v[154:157], v[226:229], v[12:15]
	v_mfma_f32_16x16x32_bf16 v[8:11], v[162:165], v[226:229], v[8:11]
	s_setprio 0
	s_setprio 1
	v_mfma_f32_16x16x32_bf16 v[52:55], v[166:169], v[182:185], v[52:55]
	v_mfma_f32_16x16x32_bf16 v[48:51], v[174:177], v[182:185], v[48:51]
	v_mfma_f32_16x16x32_bf16 v[36:39], v[166:169], v[190:193], v[36:39]
	v_mfma_f32_16x16x32_bf16 v[32:35], v[174:177], v[190:193], v[32:35]
	v_mfma_f32_16x16x32_bf16 v[20:23], v[166:169], v[198:201], v[20:23]
	v_mfma_f32_16x16x32_bf16 v[16:19], v[174:177], v[198:201], v[16:19]
	v_mfma_f32_16x16x32_bf16 v[4:7], v[166:169], v[206:209], v[4:7]
	v_mfma_f32_16x16x32_bf16 v[0:3], v[174:177], v[206:209], v[0:3]
	v_mfma_f32_16x16x32_bf16 v[52:55], v[170:173], v[186:189], v[52:55]
	v_mfma_f32_16x16x32_bf16 v[48:51], v[178:181], v[186:189], v[48:51]
	v_mfma_f32_16x16x32_bf16 v[36:39], v[170:173], v[194:197], v[36:39]
	v_mfma_f32_16x16x32_bf16 v[32:35], v[178:181], v[194:197], v[32:35]
	v_mfma_f32_16x16x32_bf16 v[20:23], v[170:173], v[202:205], v[20:23]
	v_mfma_f32_16x16x32_bf16 v[16:19], v[178:181], v[202:205], v[16:19]
	v_mfma_f32_16x16x32_bf16 v[4:7], v[170:173], v[226:229], v[4:7]
	v_mfma_f32_16x16x32_bf16 v[0:3], v[178:181], v[226:229], v[0:3]
	s_setprio 0
	s_add_i32 s11, s11, 2
	s_add_u32 s52, s52, 0x100
	s_addc_u32 s53, s53, 0
	s_cmp_gt_u32 s11, 61
	s_barrier
	s_cbranch_scc0 .LBB0_572
	s_add_u32 s28, s5, 0xffffff00
	s_addc_u32 s29, s6, -1
	s_andn2_b64 vcc, exec, s[0:1]
	s_cbranch_vccnz .LBB0_575
	v_mov_b32_e32 v0, 0
	s_mov_b32 s40, s44
	s_mov_b32 s67, s46
	s_mov_b64 s[22:23], s[50:51]
	s_mov_b32 s56, s4
	v_mov_b32_e32 v1, v0
	v_mov_b32_e32 v2, v0
	v_mov_b32_e32 v3, v0
	v_mov_b32_e32 v4, v0
	v_mov_b32_e32 v5, v0
	v_mov_b32_e32 v6, v0
	v_mov_b32_e32 v7, v0
	v_mov_b32_e32 v16, v0
	v_mov_b32_e32 v17, v0
	v_mov_b32_e32 v18, v0
	v_mov_b32_e32 v19, v0
	v_mov_b32_e32 v20, v0
	v_mov_b32_e32 v21, v0
	v_mov_b32_e32 v22, v0
	v_mov_b32_e32 v23, v0
	v_mov_b32_e32 v32, v0
	v_mov_b32_e32 v33, v0
	v_mov_b32_e32 v34, v0
	v_mov_b32_e32 v35, v0
	v_mov_b32_e32 v36, v0
	v_mov_b32_e32 v37, v0
	v_mov_b32_e32 v38, v0
	v_mov_b32_e32 v39, v0
	v_mov_b32_e32 v48, v0
	v_mov_b32_e32 v49, v0
	v_mov_b32_e32 v50, v0
	v_mov_b32_e32 v51, v0
	v_mov_b32_e32 v52, v0
	v_mov_b32_e32 v53, v0
	v_mov_b32_e32 v54, v0
	v_mov_b32_e32 v55, v0
	v_mov_b32_e32 v8, v0
	v_mov_b32_e32 v9, v0
	v_mov_b32_e32 v10, v0
	v_mov_b32_e32 v11, v0
	v_mov_b32_e32 v12, v0
	v_mov_b32_e32 v13, v0
	v_mov_b32_e32 v14, v0
	v_mov_b32_e32 v15, v0
	v_mov_b32_e32 v24, v0
	v_mov_b32_e32 v25, v0
	v_mov_b32_e32 v26, v0
	v_mov_b32_e32 v27, v0
	v_mov_b32_e32 v28, v0
	v_mov_b32_e32 v29, v0
	v_mov_b32_e32 v30, v0
	v_mov_b32_e32 v31, v0
	v_mov_b32_e32 v40, v0
	v_mov_b32_e32 v41, v0
	v_mov_b32_e32 v42, v0
	v_mov_b32_e32 v43, v0
	v_mov_b32_e32 v44, v0
	v_mov_b32_e32 v45, v0
	v_mov_b32_e32 v46, v0
	v_mov_b32_e32 v47, v0
	v_mov_b32_e32 v56, v0
	v_mov_b32_e32 v57, v0
	v_mov_b32_e32 v58, v0
	v_mov_b32_e32 v59, v0
	v_mov_b32_e32 v60, v0
	v_mov_b32_e32 v61, v0
	v_mov_b32_e32 v62, v0
	v_mov_b32_e32 v63, v0
	v_mov_b32_e32 v66, v0
	v_mov_b32_e32 v67, v0
	v_mov_b32_e32 v68, v0
	v_mov_b32_e32 v69, v0
	v_mov_b32_e32 v70, v0
	v_mov_b32_e32 v71, v0
	v_mov_b32_e32 v72, v0
	v_mov_b32_e32 v73, v0
	v_mov_b32_e32 v86, v0
	v_mov_b32_e32 v87, v0
	v_mov_b32_e32 v88, v0
	v_mov_b32_e32 v89, v0
	v_mov_b32_e32 v94, v0
	v_mov_b32_e32 v95, v0
	v_mov_b32_e32 v96, v0
	v_mov_b32_e32 v97, v0
	v_mov_b32_e32 v114, v0
	v_mov_b32_e32 v115, v0
	v_mov_b32_e32 v116, v0
	v_mov_b32_e32 v117, v0
	v_mov_b32_e32 v118, v0
	v_mov_b32_e32 v119, v0
	v_mov_b32_e32 v120, v0
	v_mov_b32_e32 v121, v0
	v_mov_b32_e32 v130, v0
	v_mov_b32_e32 v131, v0
	v_mov_b32_e32 v132, v0
	v_mov_b32_e32 v133, v0
	v_mov_b32_e32 v138, v0
	v_mov_b32_e32 v139, v0
	v_mov_b32_e32 v140, v0
	v_mov_b32_e32 v141, v0
	v_mov_b32_e32 v74, v0
	v_mov_b32_e32 v75, v0
	v_mov_b32_e32 v76, v0
	v_mov_b32_e32 v77, v0
	v_mov_b32_e32 v78, v0
	v_mov_b32_e32 v79, v0
	v_mov_b32_e32 v80, v0
	v_mov_b32_e32 v81, v0
	v_mov_b32_e32 v106, v0
	v_mov_b32_e32 v107, v0
	v_mov_b32_e32 v108, v0
	v_mov_b32_e32 v109, v0
	v_mov_b32_e32 v110, v0
	v_mov_b32_e32 v111, v0
	v_mov_b32_e32 v112, v0
	v_mov_b32_e32 v113, v0
	v_mov_b32_e32 v122, v0
	v_mov_b32_e32 v123, v0
	v_mov_b32_e32 v124, v0
	v_mov_b32_e32 v125, v0
	v_mov_b32_e32 v126, v0
	v_mov_b32_e32 v127, v0
	v_mov_b32_e32 v128, v0
	v_mov_b32_e32 v129, v0
	v_mov_b32_e32 v142, v0
	v_mov_b32_e32 v143, v0
	v_mov_b32_e32 v144, v0
	v_mov_b32_e32 v145, v0
	v_mov_b32_e32 v134, v0
	v_mov_b32_e32 v135, v0
	v_mov_b32_e32 v136, v0
	v_mov_b32_e32 v137, v0
	s_andn2_b64 vcc, exec, s[42:43]
	s_cbranch_vccnz .LBB0_576
	s_branch .LBB0_577

.LBB0_789:
	s_add_u32 s10, s52, 0xfffc0080
	s_addc_u32 s11, s53, -1
	s_add_i32 s12, 0, 0x10000
	s_cmp_eq_u32 s9, 12
	s_cselect_b32 s37, s1, s11
	s_cselect_b32 s36, s4, s10
	s_cselect_b32 s29, s5, s8
	s_cselect_b32 s28, s6, s7
	s_add_i32 s13, 0, 0x14000
	v_add_u32_e32 v142, s12, v181
	v_add_u32_e32 v168, s13, v181
	ds_read_b128 v[130:133], v142
	ds_read_b128 v[134:137], v142 offset:1024
	ds_read_b128 v[138:141], v142 offset:2048
	ds_read_b128 v[142:145], v142 offset:3072
	ds_read_b128 v[146:149], v168
	ds_read_b128 v[160:163], v168 offset:1024
	ds_read_b128 v[164:167], v168 offset:2048
	ds_read_b128 v[168:171], v168 offset:3072
	s_mov_b32 m0, s80
	v_lshl_add_u64 v[176:177], s[52:53], 0, v[156:157]
	ds_read_b128 v[172:175], v184
	ds_read_b128 v[186:189], v184 offset:1024
	ds_read_b128 v[190:193], v184 offset:2048
	ds_read_b128 v[194:197], v184 offset:3072
	ds_read_b128 v[198:201], v184 offset:4096
	ds_read_b128 v[202:205], v184 offset:5120
	ds_read_b128 v[206:209], v184 offset:6144
	ds_read_b128 v[226:229], v184 offset:7168
	global_load_lds_dwordx4 v[176:177], off
	v_lshl_add_u64 v[176:177], s[52:53], 0, v[158:159]
	s_add_i32 m0, s25, 0xe000
	s_nop 0
	global_load_lds_dwordx4 v[176:177], off
	s_waitcnt vmcnt(8)
	s_waitcnt lgkmcnt(0)
	s_barrier
	s_setprio 1
	s_waitcnt lgkmcnt(0)
	v_mfma_f32_16x16x32_bf16 v[126:129], v[130:133], v[172:175], v[126:129]
	v_mfma_f32_16x16x32_bf16 v[122:125], v[138:141], v[172:175], v[122:125]
	v_mfma_f32_16x16x32_bf16 v[114:117], v[130:133], v[190:193], v[114:117]
	v_mfma_f32_16x16x32_bf16 v[106:109], v[138:141], v[190:193], v[106:109]
	v_mfma_f32_16x16x32_bf16 v[98:101], v[130:133], v[198:201], v[98:101]
	v_mfma_f32_16x16x32_bf16 v[90:93], v[138:141], v[198:201], v[90:93]
	v_mfma_f32_16x16x32_bf16 v[82:85], v[130:133], v[206:209], v[82:85]
	v_mfma_f32_16x16x32_bf16 v[74:77], v[138:141], v[206:209], v[74:77]
	v_mfma_f32_16x16x32_bf16 v[126:129], v[134:137], v[186:189], v[126:129]
	v_mfma_f32_16x16x32_bf16 v[122:125], v[142:145], v[186:189], v[122:125]
	v_mfma_f32_16x16x32_bf16 v[114:117], v[134:137], v[194:197], v[114:117]
	v_mfma_f32_16x16x32_bf16 v[106:109], v[142:145], v[194:197], v[106:109]
	v_mfma_f32_16x16x32_bf16 v[98:101], v[134:137], v[202:205], v[98:101]
	v_mfma_f32_16x16x32_bf16 v[90:93], v[142:145], v[202:205], v[90:93]
	v_mfma_f32_16x16x32_bf16 v[82:85], v[134:137], v[226:229], v[82:85]
	v_mfma_f32_16x16x32_bf16 v[74:77], v[142:145], v[226:229], v[74:77]
	s_setprio 0
	s_setprio 1
	v_mfma_f32_16x16x32_bf16 v[118:121], v[146:149], v[172:175], v[118:121]
	v_mfma_f32_16x16x32_bf16 v[110:113], v[164:167], v[172:175], v[110:113]
	v_mfma_f32_16x16x32_bf16 v[102:105], v[146:149], v[190:193], v[102:105]
	v_mfma_f32_16x16x32_bf16 v[94:97], v[164:167], v[190:193], v[94:97]
	v_mfma_f32_16x16x32_bf16 v[86:89], v[146:149], v[198:201], v[86:89]
	v_mfma_f32_16x16x32_bf16 v[78:81], v[164:167], v[198:201], v[78:81]
	v_mfma_f32_16x16x32_bf16 v[70:73], v[146:149], v[206:209], v[70:73]
	v_mfma_f32_16x16x32_bf16 v[66:69], v[164:167], v[206:209], v[66:69]
	v_mfma_f32_16x16x32_bf16 v[118:121], v[160:163], v[186:189], v[118:121]
	v_mfma_f32_16x16x32_bf16 v[110:113], v[168:171], v[186:189], v[110:113]
	v_mfma_f32_16x16x32_bf16 v[102:105], v[160:163], v[194:197], v[102:105]
	v_mfma_f32_16x16x32_bf16 v[94:97], v[168:171], v[194:197], v[94:97]
	v_mfma_f32_16x16x32_bf16 v[86:89], v[160:163], v[202:205], v[86:89]
	v_mfma_f32_16x16x32_bf16 v[78:81], v[168:171], v[202:205], v[78:81]
	v_mfma_f32_16x16x32_bf16 v[70:73], v[160:163], v[226:229], v[70:73]
	v_mfma_f32_16x16x32_bf16 v[66:69], v[168:171], v[226:229], v[66:69]
	s_setprio 0
	s_barrier
	s_add_i32 s10, s12, s38
	v_lshl_add_u64 v[176:177], s[28:29], 0, v[64:65]
	s_mov_b32 m0, s10
	ds_read_b128 v[172:175], v184 offset:16384
	ds_read_b128 v[186:189], v184 offset:17408
	ds_read_b128 v[190:193], v184 offset:18432
	ds_read_b128 v[194:197], v184 offset:19456
	ds_read_b128 v[198:201], v184 offset:20480
	ds_read_b128 v[202:205], v184 offset:21504
	ds_read_b128 v[206:209], v184 offset:22528
	ds_read_b128 v[226:229], v184 offset:23552
	global_load_lds_dwordx4 v[176:177], off
	s_add_i32 m0, s10, 0x2000
	s_add_u32 s10, s28, 0x40000
	v_lshl_add_u64 v[230:231], s[28:29], 0, v[154:155]
	s_addc_u32 s11, s29, 0
	s_add_i32 s12, s13, s38
	global_load_lds_dwordx4 v[230:231], off
	v_lshl_add_u64 v[232:233], s[10:11], 0, v[64:65]
	s_mov_b32 m0, s12
	v_lshl_add_u64 v[244:245], s[36:37], 0, v[152:153]
	global_load_lds_dwordx4 v[232:233], off
	v_lshl_add_u64 v[232:233], s[10:11], 0, v[154:155]
	s_add_i32 m0, s12, 0x2000
	v_readlane_b32 s10, v251, 21
	global_load_lds_dwordx4 v[232:233], off
	v_lshl_add_u64 v[232:233], s[36:37], 0, v[150:151]
	s_mov_b32 m0, s25
	s_nop 0
	global_load_lds_dwordx4 v[232:233], off
	s_mov_b32 m0, s10
	s_nop 0
	global_load_lds_dwordx4 v[244:245], off
	s_waitcnt vmcnt(8)
	s_waitcnt lgkmcnt(0)
	s_barrier
	s_setprio 1
	s_waitcnt lgkmcnt(0)
	v_mfma_f32_16x16x32_bf16 v[60:63], v[130:133], v[172:175], v[60:63]
	v_mfma_f32_16x16x32_bf16 v[56:59], v[138:141], v[172:175], v[56:59]
	v_mfma_f32_16x16x32_bf16 v[48:51], v[130:133], v[190:193], v[48:51]
	v_mfma_f32_16x16x32_bf16 v[40:43], v[138:141], v[190:193], v[40:43]
	v_mfma_f32_16x16x32_bf16 v[32:35], v[130:133], v[198:201], v[32:35]
	v_mfma_f32_16x16x32_bf16 v[24:27], v[138:141], v[198:201], v[24:27]
	v_mfma_f32_16x16x32_bf16 v[16:19], v[130:133], v[206:209], v[16:19]
	v_mfma_f32_16x16x32_bf16 v[8:11], v[138:141], v[206:209], v[8:11]
	v_mfma_f32_16x16x32_bf16 v[60:63], v[134:137], v[186:189], v[60:63]
	v_mfma_f32_16x16x32_bf16 v[56:59], v[142:145], v[186:189], v[56:59]
	v_mfma_f32_16x16x32_bf16 v[48:51], v[134:137], v[194:197], v[48:51]
	v_mfma_f32_16x16x32_bf16 v[40:43], v[142:145], v[194:197], v[40:43]
	v_mfma_f32_16x16x32_bf16 v[32:35], v[134:137], v[202:205], v[32:35]
	v_mfma_f32_16x16x32_bf16 v[24:27], v[142:145], v[202:205], v[24:27]
	v_mfma_f32_16x16x32_bf16 v[16:19], v[134:137], v[226:229], v[16:19]
	v_mfma_f32_16x16x32_bf16 v[8:11], v[142:145], v[226:229], v[8:11]
	s_setprio 0
	s_setprio 1
	v_mfma_f32_16x16x32_bf16 v[52:55], v[146:149], v[172:175], v[52:55]
	v_mfma_f32_16x16x32_bf16 v[44:47], v[164:167], v[172:175], v[44:47]
	v_mfma_f32_16x16x32_bf16 v[36:39], v[146:149], v[190:193], v[36:39]
	v_mfma_f32_16x16x32_bf16 v[28:31], v[164:167], v[190:193], v[28:31]
	v_mfma_f32_16x16x32_bf16 v[20:23], v[146:149], v[198:201], v[20:23]
	v_mfma_f32_16x16x32_bf16 v[12:15], v[164:167], v[198:201], v[12:15]
	v_mfma_f32_16x16x32_bf16 v[4:7], v[146:149], v[206:209], v[4:7]
	v_mfma_f32_16x16x32_bf16 v[0:3], v[164:167], v[206:209], v[0:3]
	v_mfma_f32_16x16x32_bf16 v[52:55], v[160:163], v[186:189], v[52:55]
	v_mfma_f32_16x16x32_bf16 v[44:47], v[168:171], v[186:189], v[44:47]
	v_mfma_f32_16x16x32_bf16 v[36:39], v[160:163], v[194:197], v[36:39]
	v_mfma_f32_16x16x32_bf16 v[28:31], v[168:171], v[194:197], v[28:31]
	v_mfma_f32_16x16x32_bf16 v[20:23], v[160:163], v[202:205], v[20:23]
	v_mfma_f32_16x16x32_bf16 v[12:15], v[168:171], v[202:205], v[12:15]
	v_mfma_f32_16x16x32_bf16 v[4:7], v[160:163], v[226:229], v[4:7]
	v_mfma_f32_16x16x32_bf16 v[0:3], v[168:171], v[226:229], v[0:3]
	s_setprio 0
	s_barrier
	s_add_i32 s12, 0, 0x18000
	s_add_i32 s13, 0, 0x1c000
	v_add_u32_e32 v142, s12, v181
	v_add_u32_e32 v168, s13, v181
	ds_read_b128 v[130:133], v142
	ds_read_b128 v[134:137], v142 offset:1024
	ds_read_b128 v[138:141], v142 offset:2048
	ds_read_b128 v[142:145], v142 offset:3072
	ds_read_b128 v[146:149], v168
	ds_read_b128 v[160:163], v168 offset:1024
	ds_read_b128 v[164:167], v168 offset:2048
	ds_read_b128 v[168:171], v168 offset:3072
	s_add_u32 s10, s36, 0x40000
	s_addc_u32 s11, s37, 0
	s_mov_b32 m0, s75
	v_lshl_add_u64 v[210:211], s[10:11], 0, v[150:151]
	ds_read_b128 v[172:175], v184 offset:32768
	ds_read_b128 v[186:189], v184 offset:33792
	ds_read_b128 v[190:193], v184 offset:34816
	ds_read_b128 v[194:197], v184 offset:35840
	ds_read_b128 v[198:201], v184 offset:36864
	ds_read_b128 v[202:205], v184 offset:37888
	ds_read_b128 v[206:209], v184 offset:38912
	ds_read_b128 v[226:229], v184 offset:39936
	global_load_lds_dwordx4 v[210:211], off
	v_lshl_add_u64 v[210:211], s[10:11], 0, v[152:153]
	s_mov_b32 m0, s74
	s_nop 0
	global_load_lds_dwordx4 v[210:211], off
	s_waitcnt vmcnt(8)
	s_waitcnt lgkmcnt(0)
	s_barrier
	s_setprio 1
	s_waitcnt lgkmcnt(0)
	v_mfma_f32_16x16x32_bf16 v[126:129], v[130:133], v[172:175], v[126:129]
	v_mfma_f32_16x16x32_bf16 v[122:125], v[138:141], v[172:175], v[122:125]
	v_mfma_f32_16x16x32_bf16 v[114:117], v[130:133], v[190:193], v[114:117]
	v_mfma_f32_16x16x32_bf16 v[106:109], v[138:141], v[190:193], v[106:109]
	v_mfma_f32_16x16x32_bf16 v[98:101], v[130:133], v[198:201], v[98:101]
	v_mfma_f32_16x16x32_bf16 v[90:93], v[138:141], v[198:201], v[90:93]
	v_mfma_f32_16x16x32_bf16 v[82:85], v[130:133], v[206:209], v[82:85]
	v_mfma_f32_16x16x32_bf16 v[74:77], v[138:141], v[206:209], v[74:77]
	v_mfma_f32_16x16x32_bf16 v[126:129], v[134:137], v[186:189], v[126:129]
	v_mfma_f32_16x16x32_bf16 v[122:125], v[142:145], v[186:189], v[122:125]
	v_mfma_f32_16x16x32_bf16 v[114:117], v[134:137], v[194:197], v[114:117]
	v_mfma_f32_16x16x32_bf16 v[106:109], v[142:145], v[194:197], v[106:109]
	v_mfma_f32_16x16x32_bf16 v[98:101], v[134:137], v[202:205], v[98:101]
	v_mfma_f32_16x16x32_bf16 v[90:93], v[142:145], v[202:205], v[90:93]
	v_mfma_f32_16x16x32_bf16 v[82:85], v[134:137], v[226:229], v[82:85]
	v_mfma_f32_16x16x32_bf16 v[74:77], v[142:145], v[226:229], v[74:77]
	s_setprio 0
	s_setprio 1
	v_mfma_f32_16x16x32_bf16 v[118:121], v[146:149], v[172:175], v[118:121]
	v_mfma_f32_16x16x32_bf16 v[110:113], v[164:167], v[172:175], v[110:113]
	v_mfma_f32_16x16x32_bf16 v[102:105], v[146:149], v[190:193], v[102:105]
	v_mfma_f32_16x16x32_bf16 v[94:97], v[164:167], v[190:193], v[94:97]
	v_mfma_f32_16x16x32_bf16 v[86:89], v[146:149], v[198:201], v[86:89]
	v_mfma_f32_16x16x32_bf16 v[78:81], v[164:167], v[198:201], v[78:81]
	v_mfma_f32_16x16x32_bf16 v[70:73], v[146:149], v[206:209], v[70:73]
	v_mfma_f32_16x16x32_bf16 v[66:69], v[164:167], v[206:209], v[66:69]
	v_mfma_f32_16x16x32_bf16 v[118:121], v[160:163], v[186:189], v[118:121]
	v_mfma_f32_16x16x32_bf16 v[110:113], v[168:171], v[186:189], v[110:113]
	v_mfma_f32_16x16x32_bf16 v[102:105], v[160:163], v[194:197], v[102:105]
	v_mfma_f32_16x16x32_bf16 v[94:97], v[168:171], v[194:197], v[94:97]
	v_mfma_f32_16x16x32_bf16 v[86:89], v[160:163], v[202:205], v[86:89]
	v_mfma_f32_16x16x32_bf16 v[78:81], v[168:171], v[202:205], v[78:81]
	v_mfma_f32_16x16x32_bf16 v[70:73], v[160:163], v[226:229], v[70:73]
	v_mfma_f32_16x16x32_bf16 v[66:69], v[168:171], v[226:229], v[66:69]
	s_setprio 0
	s_barrier
	s_add_i32 s10, s12, s38
	v_lshl_add_u64 v[176:177], v[176:177], 0, s[42:43]
	s_mov_b32 m0, s10
	ds_read_b128 v[172:175], v184 offset:49152
	ds_read_b128 v[186:189], v184 offset:50176
	ds_read_b128 v[190:193], v184 offset:51200
	ds_read_b128 v[194:197], v184 offset:52224
	ds_read_b128 v[198:201], v184 offset:53248
	ds_read_b128 v[202:205], v184 offset:54272
	ds_read_b128 v[206:209], v184 offset:55296
	ds_read_b128 v[226:229], v184 offset:56320
	global_load_lds_dwordx4 v[176:177], off
	s_add_i32 m0, s10, 0x2000
	s_add_u32 s10, s28, 0x40080
	v_lshl_add_u64 v[176:177], v[230:231], 0, s[42:43]
	s_addc_u32 s11, s29, 0
	s_add_i32 s12, s13, s38
	global_load_lds_dwordx4 v[176:177], off
	v_lshl_add_u64 v[176:177], s[10:11], 0, v[64:65]
	s_mov_b32 m0, s12
	s_nop 0
	global_load_lds_dwordx4 v[176:177], off
	v_lshl_add_u64 v[176:177], s[10:11], 0, v[154:155]
	s_add_i32 m0, s12, 0x2000
	s_nop 0
	global_load_lds_dwordx4 v[176:177], off
	v_lshl_add_u64 v[176:177], v[232:233], 0, s[42:43]
	s_mov_b32 m0, s92
	s_nop 0
	global_load_lds_dwordx4 v[176:177], off
	v_lshl_add_u64 v[176:177], v[244:245], 0, s[42:43]
	s_mov_b32 m0, s78
	s_nop 0
	global_load_lds_dwordx4 v[176:177], off
	s_waitcnt vmcnt(8)
	s_waitcnt lgkmcnt(0)
	s_barrier
	s_setprio 1
	s_waitcnt lgkmcnt(0)
	v_mfma_f32_16x16x32_bf16 v[60:63], v[130:133], v[172:175], v[60:63]
	v_mfma_f32_16x16x32_bf16 v[56:59], v[138:141], v[172:175], v[56:59]
	v_mfma_f32_16x16x32_bf16 v[48:51], v[130:133], v[190:193], v[48:51]
	v_mfma_f32_16x16x32_bf16 v[40:43], v[138:141], v[190:193], v[40:43]
	v_mfma_f32_16x16x32_bf16 v[32:35], v[130:133], v[198:201], v[32:35]
	v_mfma_f32_16x16x32_bf16 v[24:27], v[138:141], v[198:201], v[24:27]
	v_mfma_f32_16x16x32_bf16 v[16:19], v[130:133], v[206:209], v[16:19]
	v_mfma_f32_16x16x32_bf16 v[8:11], v[138:141], v[206:209], v[8:11]
	v_mfma_f32_16x16x32_bf16 v[60:63], v[134:137], v[186:189], v[60:63]
	v_mfma_f32_16x16x32_bf16 v[56:59], v[142:145], v[186:189], v[56:59]
	v_mfma_f32_16x16x32_bf16 v[48:51], v[134:137], v[194:197], v[48:51]
	v_mfma_f32_16x16x32_bf16 v[40:43], v[142:145], v[194:197], v[40:43]
	v_mfma_f32_16x16x32_bf16 v[32:35], v[134:137], v[202:205], v[32:35]
	v_mfma_f32_16x16x32_bf16 v[24:27], v[142:145], v[202:205], v[24:27]
	v_mfma_f32_16x16x32_bf16 v[16:19], v[134:137], v[226:229], v[16:19]
	v_mfma_f32_16x16x32_bf16 v[8:11], v[142:145], v[226:229], v[8:11]
	s_setprio 0
	s_setprio 1
	v_mfma_f32_16x16x32_bf16 v[52:55], v[146:149], v[172:175], v[52:55]
	v_mfma_f32_16x16x32_bf16 v[44:47], v[164:167], v[172:175], v[44:47]
	v_mfma_f32_16x16x32_bf16 v[36:39], v[146:149], v[190:193], v[36:39]
	v_mfma_f32_16x16x32_bf16 v[28:31], v[164:167], v[190:193], v[28:31]
	v_mfma_f32_16x16x32_bf16 v[20:23], v[146:149], v[198:201], v[20:23]
	v_mfma_f32_16x16x32_bf16 v[12:15], v[164:167], v[198:201], v[12:15]
	v_mfma_f32_16x16x32_bf16 v[4:7], v[146:149], v[206:209], v[4:7]
	v_mfma_f32_16x16x32_bf16 v[0:3], v[164:167], v[206:209], v[0:3]
	v_mfma_f32_16x16x32_bf16 v[52:55], v[160:163], v[186:189], v[52:55]
	v_mfma_f32_16x16x32_bf16 v[44:47], v[168:171], v[186:189], v[44:47]
	v_mfma_f32_16x16x32_bf16 v[36:39], v[160:163], v[194:197], v[36:39]
	v_mfma_f32_16x16x32_bf16 v[28:31], v[168:171], v[194:197], v[28:31]
	v_mfma_f32_16x16x32_bf16 v[20:23], v[160:163], v[202:205], v[20:23]
	v_mfma_f32_16x16x32_bf16 v[12:15], v[168:171], v[202:205], v[12:15]
	v_mfma_f32_16x16x32_bf16 v[4:7], v[160:163], v[226:229], v[4:7]
	v_mfma_f32_16x16x32_bf16 v[0:3], v[168:171], v[226:229], v[0:3]
	s_setprio 0
	s_add_i32 s9, s9, 2
	s_add_u32 s52, s52, 0x100
	s_addc_u32 s53, s53, 0
	s_add_u32 s7, s7, 0x100
	s_addc_u32 s8, s8, 0
	s_cmp_gt_u32 s9, 13
	s_barrier
	s_cbranch_scc0 .LBB0_789
	s_and_b64 vcc, exec, s[18:19]
	s_cbranch_vccz .LBB0_792
	s_barrier
